# hand-written residual epilogues (batched loads, fma, stores; atomics for split-K parts) for ffdown0, odout, ffdown1 replacing serialized load-wait-store chains
# speedup vs baseline: 1.0942x; 1.0402x over previous
.LBB0_1107:
	v_lshl_or_b32 v138, v183, 3, v191
	v_and_b32_e32 v139, 31, v138
	v_bfe_u32 v140, v138, 6, 1
	v_mul_u32_u24_e32 v140, 64, v140
	v_add_u32_e32 v140, v140, v139
	v_lshlrev_b32_e32 v142, 2, v140
	v_bfe_u32 v140, v138, 7, 1
	v_lshlrev_b32_e32 v140, 4, v140
	v_bfe_u32 v145, v138, 5, 1
	v_or_b32_e32 v140, v140, v145
	v_lshl_add_u32 v141, v140, 14, v142
	s_sub_u32 s100, s9, 0x2000
	s_lshr_b32 s100, s100, 11
	s_add_u32 s100, s100, 1
	s_cmp_lt_u32 s9, 0x2000
	s_cmov_b32 s100, 0
	s_mul_i32 s100, s100, 0x6000
	s_lshl_b32 s101, s10, 2
	s_add_u32 s100, s100, s101
	s_add_u32 s100, s100, 0x3445000
	v_add_u32_e32 v142, s100, v142
	global_load_dword v143, v142, s[90:91]
	global_load_dword v144, v142, s[90:91] offset:128
	s_lshl_b32 s100, s9, 12
	s_add_u32 s100, s100, s101
	s_add_u32 s98, s88, s100
	s_addc_u32 s99, s89, 0
	s_and_b64 vcc, exec, s[36:37]
	s_cbranch_vccnz .Lep3_part
	s_mov_b32 s2, s98
	s_mov_b32 s3, s99
	global_load_dword v64, v141, s[2:3] offset:0
	global_load_dword v65, v141, s[2:3] offset:128
	s_add_u32 s2, s2, 0x1000
	s_addc_u32 s3, s3, 0
	global_load_dword v66, v141, s[2:3] offset:0
	global_load_dword v67, v141, s[2:3] offset:128
	s_add_u32 s2, s2, 0x1000
	s_addc_u32 s3, s3, 0
	global_load_dword v68, v141, s[2:3] offset:0
	global_load_dword v69, v141, s[2:3] offset:128
	s_add_u32 s2, s2, 0x1000
	s_addc_u32 s3, s3, 0
	global_load_dword v70, v141, s[2:3] offset:0
	global_load_dword v71, v141, s[2:3] offset:128
	s_add_u32 s2, s2, 0x5000
	s_addc_u32 s3, s3, 0
	global_load_dword v72, v141, s[2:3] offset:0
	global_load_dword v73, v141, s[2:3] offset:128
	s_add_u32 s2, s2, 0x1000
	s_addc_u32 s3, s3, 0
	global_load_dword v74, v141, s[2:3] offset:0
	global_load_dword v75, v141, s[2:3] offset:128
	s_add_u32 s2, s2, 0x1000
	s_addc_u32 s3, s3, 0
	global_load_dword v76, v141, s[2:3] offset:0
	global_load_dword v77, v141, s[2:3] offset:128
	s_add_u32 s2, s2, 0x1000
	s_addc_u32 s3, s3, 0
	global_load_dword v78, v141, s[2:3] offset:0
	global_load_dword v79, v141, s[2:3] offset:128
	s_add_u32 s2, s2, 0x5000
	s_addc_u32 s3, s3, 0
	global_load_dword v80, v141, s[2:3] offset:0
	global_load_dword v81, v141, s[2:3] offset:128
	s_add_u32 s2, s2, 0x1000
	s_addc_u32 s3, s3, 0
	global_load_dword v82, v141, s[2:3] offset:0
	global_load_dword v83, v141, s[2:3] offset:128
	s_add_u32 s2, s2, 0x1000
	s_addc_u32 s3, s3, 0
	global_load_dword v84, v141, s[2:3] offset:0
	global_load_dword v85, v141, s[2:3] offset:128
	s_add_u32 s2, s2, 0x1000
	s_addc_u32 s3, s3, 0
	global_load_dword v86, v141, s[2:3] offset:0
	global_load_dword v87, v141, s[2:3] offset:128
	s_add_u32 s2, s2, 0x5000
	s_addc_u32 s3, s3, 0
	global_load_dword v88, v141, s[2:3] offset:0
	global_load_dword v89, v141, s[2:3] offset:128
	s_add_u32 s2, s2, 0x1000
	s_addc_u32 s3, s3, 0
	global_load_dword v90, v141, s[2:3] offset:0
	global_load_dword v91, v141, s[2:3] offset:128
	s_add_u32 s2, s2, 0x1000
	s_addc_u32 s3, s3, 0
	global_load_dword v92, v141, s[2:3] offset:0
	global_load_dword v93, v141, s[2:3] offset:128
	s_add_u32 s2, s2, 0x1000
	s_addc_u32 s3, s3, 0
	global_load_dword v94, v141, s[2:3] offset:0
	global_load_dword v95, v141, s[2:3] offset:128
	s_add_u32 s2, s2, 0x5000
	s_addc_u32 s3, s3, 0
	global_load_dword v96, v141, s[2:3] offset:0
	global_load_dword v97, v141, s[2:3] offset:128
	s_add_u32 s2, s2, 0x1000
	s_addc_u32 s3, s3, 0
	global_load_dword v98, v141, s[2:3] offset:0
	global_load_dword v99, v141, s[2:3] offset:128
	s_add_u32 s2, s2, 0x1000
	s_addc_u32 s3, s3, 0
	global_load_dword v100, v141, s[2:3] offset:0
	global_load_dword v101, v141, s[2:3] offset:128
	s_add_u32 s2, s2, 0x1000
	s_addc_u32 s3, s3, 0
	global_load_dword v102, v141, s[2:3] offset:0
	global_load_dword v103, v141, s[2:3] offset:128
	s_add_u32 s2, s2, 0x5000
	s_addc_u32 s3, s3, 0
	global_load_dword v104, v141, s[2:3] offset:0
	global_load_dword v105, v141, s[2:3] offset:128
	s_add_u32 s2, s2, 0x1000
	s_addc_u32 s3, s3, 0
	global_load_dword v106, v141, s[2:3] offset:0
	global_load_dword v107, v141, s[2:3] offset:128
	s_add_u32 s2, s2, 0x1000
	s_addc_u32 s3, s3, 0
	global_load_dword v108, v141, s[2:3] offset:0
	global_load_dword v109, v141, s[2:3] offset:128
	s_add_u32 s2, s2, 0x1000
	s_addc_u32 s3, s3, 0
	global_load_dword v110, v141, s[2:3] offset:0
	global_load_dword v111, v141, s[2:3] offset:128
	s_add_u32 s2, s2, 0x5000
	s_addc_u32 s3, s3, 0
	global_load_dword v112, v141, s[2:3] offset:0
	global_load_dword v113, v141, s[2:3] offset:128
	s_add_u32 s2, s2, 0x1000
	s_addc_u32 s3, s3, 0
	global_load_dword v114, v141, s[2:3] offset:0
	global_load_dword v115, v141, s[2:3] offset:128
	s_add_u32 s2, s2, 0x1000
	s_addc_u32 s3, s3, 0
	global_load_dword v116, v141, s[2:3] offset:0
	global_load_dword v117, v141, s[2:3] offset:128
	s_add_u32 s2, s2, 0x1000
	s_addc_u32 s3, s3, 0
	global_load_dword v118, v141, s[2:3] offset:0
	global_load_dword v119, v141, s[2:3] offset:128
	s_add_u32 s2, s2, 0x5000
	s_addc_u32 s3, s3, 0
	global_load_dword v120, v141, s[2:3] offset:0
	global_load_dword v121, v141, s[2:3] offset:128
	s_add_u32 s2, s2, 0x1000
	s_addc_u32 s3, s3, 0
	global_load_dword v122, v141, s[2:3] offset:0
	global_load_dword v123, v141, s[2:3] offset:128
	s_add_u32 s2, s2, 0x1000
	s_addc_u32 s3, s3, 0
	global_load_dword v124, v141, s[2:3] offset:0
	global_load_dword v125, v141, s[2:3] offset:128
	s_add_u32 s2, s2, 0x1000
	s_addc_u32 s3, s3, 0
	global_load_dword v126, v141, s[2:3] offset:0
	global_load_dword v127, v141, s[2:3] offset:128
	s_waitcnt vmcnt(0)
	v_fmac_f32_e32 v64, v143, v48
	v_fmac_f32_e32 v65, v144, v16
	v_fmac_f32_e32 v66, v143, v49
	v_fmac_f32_e32 v67, v144, v17
	v_fmac_f32_e32 v68, v143, v50
	v_fmac_f32_e32 v69, v144, v18
	v_fmac_f32_e32 v70, v143, v51
	v_fmac_f32_e32 v71, v144, v19
	v_fmac_f32_e32 v72, v143, v52
	v_fmac_f32_e32 v73, v144, v20
	v_fmac_f32_e32 v74, v143, v53
	v_fmac_f32_e32 v75, v144, v21
	v_fmac_f32_e32 v76, v143, v54
	v_fmac_f32_e32 v77, v144, v22
	v_fmac_f32_e32 v78, v143, v55
	v_fmac_f32_e32 v79, v144, v23
	v_fmac_f32_e32 v80, v143, v56
	v_fmac_f32_e32 v81, v144, v24
	v_fmac_f32_e32 v82, v143, v57
	v_fmac_f32_e32 v83, v144, v25
	v_fmac_f32_e32 v84, v143, v58
	v_fmac_f32_e32 v85, v144, v26
	v_fmac_f32_e32 v86, v143, v59
	v_fmac_f32_e32 v87, v144, v27
	v_fmac_f32_e32 v88, v143, v60
	v_fmac_f32_e32 v89, v144, v28
	v_fmac_f32_e32 v90, v143, v61
	v_fmac_f32_e32 v91, v144, v29
	v_fmac_f32_e32 v92, v143, v62
	v_fmac_f32_e32 v93, v144, v30
	v_fmac_f32_e32 v94, v143, v63
	v_fmac_f32_e32 v95, v144, v31
	v_fmac_f32_e32 v96, v143, v32
	v_fmac_f32_e32 v97, v144, v0
	v_fmac_f32_e32 v98, v143, v33
	v_fmac_f32_e32 v99, v144, v1
	v_fmac_f32_e32 v100, v143, v34
	v_fmac_f32_e32 v101, v144, v2
	v_fmac_f32_e32 v102, v143, v35
	v_fmac_f32_e32 v103, v144, v3
	v_fmac_f32_e32 v104, v143, v36
	v_fmac_f32_e32 v105, v144, v4
	v_fmac_f32_e32 v106, v143, v37
	v_fmac_f32_e32 v107, v144, v5
	v_fmac_f32_e32 v108, v143, v38
	v_fmac_f32_e32 v109, v144, v6
	v_fmac_f32_e32 v110, v143, v39
	v_fmac_f32_e32 v111, v144, v7
	v_fmac_f32_e32 v112, v143, v40
	v_fmac_f32_e32 v113, v144, v8
	v_fmac_f32_e32 v114, v143, v41
	v_fmac_f32_e32 v115, v144, v9
	v_fmac_f32_e32 v116, v143, v42
	v_fmac_f32_e32 v117, v144, v10
	v_fmac_f32_e32 v118, v143, v43
	v_fmac_f32_e32 v119, v144, v11
	v_fmac_f32_e32 v120, v143, v44
	v_fmac_f32_e32 v121, v144, v12
	v_fmac_f32_e32 v122, v143, v45
	v_fmac_f32_e32 v123, v144, v13
	v_fmac_f32_e32 v124, v143, v46
	v_fmac_f32_e32 v125, v144, v14
	v_fmac_f32_e32 v126, v143, v47
	v_fmac_f32_e32 v127, v144, v15
	s_mov_b32 s2, s98
	s_mov_b32 s3, s99
	global_store_dword v141, v64, s[2:3] offset:0
	global_store_dword v141, v65, s[2:3] offset:128
	s_add_u32 s2, s2, 0x1000
	s_addc_u32 s3, s3, 0
	global_store_dword v141, v66, s[2:3] offset:0
	global_store_dword v141, v67, s[2:3] offset:128
	s_add_u32 s2, s2, 0x1000
	s_addc_u32 s3, s3, 0
	global_store_dword v141, v68, s[2:3] offset:0
	global_store_dword v141, v69, s[2:3] offset:128
	s_add_u32 s2, s2, 0x1000
	s_addc_u32 s3, s3, 0
	global_store_dword v141, v70, s[2:3] offset:0
	global_store_dword v141, v71, s[2:3] offset:128
	s_add_u32 s2, s2, 0x5000
	s_addc_u32 s3, s3, 0
	global_store_dword v141, v72, s[2:3] offset:0
	global_store_dword v141, v73, s[2:3] offset:128
	s_add_u32 s2, s2, 0x1000
	s_addc_u32 s3, s3, 0
	global_store_dword v141, v74, s[2:3] offset:0
	global_store_dword v141, v75, s[2:3] offset:128
	s_add_u32 s2, s2, 0x1000
	s_addc_u32 s3, s3, 0
	global_store_dword v141, v76, s[2:3] offset:0
	global_store_dword v141, v77, s[2:3] offset:128
	s_add_u32 s2, s2, 0x1000
	s_addc_u32 s3, s3, 0
	global_store_dword v141, v78, s[2:3] offset:0
	global_store_dword v141, v79, s[2:3] offset:128
	s_add_u32 s2, s2, 0x5000
	s_addc_u32 s3, s3, 0
	global_store_dword v141, v80, s[2:3] offset:0
	global_store_dword v141, v81, s[2:3] offset:128
	s_add_u32 s2, s2, 0x1000
	s_addc_u32 s3, s3, 0
	global_store_dword v141, v82, s[2:3] offset:0
	global_store_dword v141, v83, s[2:3] offset:128
	s_add_u32 s2, s2, 0x1000
	s_addc_u32 s3, s3, 0
	global_store_dword v141, v84, s[2:3] offset:0
	global_store_dword v141, v85, s[2:3] offset:128
	s_add_u32 s2, s2, 0x1000
	s_addc_u32 s3, s3, 0
	global_store_dword v141, v86, s[2:3] offset:0
	global_store_dword v141, v87, s[2:3] offset:128
	s_add_u32 s2, s2, 0x5000
	s_addc_u32 s3, s3, 0
	global_store_dword v141, v88, s[2:3] offset:0
	global_store_dword v141, v89, s[2:3] offset:128
	s_add_u32 s2, s2, 0x1000
	s_addc_u32 s3, s3, 0
	global_store_dword v141, v90, s[2:3] offset:0
	global_store_dword v141, v91, s[2:3] offset:128
	s_add_u32 s2, s2, 0x1000
	s_addc_u32 s3, s3, 0
	global_store_dword v141, v92, s[2:3] offset:0
	global_store_dword v141, v93, s[2:3] offset:128
	s_add_u32 s2, s2, 0x1000
	s_addc_u32 s3, s3, 0
	global_store_dword v141, v94, s[2:3] offset:0
	global_store_dword v141, v95, s[2:3] offset:128
	s_add_u32 s2, s2, 0x5000
	s_addc_u32 s3, s3, 0
	global_store_dword v141, v96, s[2:3] offset:0
	global_store_dword v141, v97, s[2:3] offset:128
	s_add_u32 s2, s2, 0x1000
	s_addc_u32 s3, s3, 0
	global_store_dword v141, v98, s[2:3] offset:0
	global_store_dword v141, v99, s[2:3] offset:128
	s_add_u32 s2, s2, 0x1000
	s_addc_u32 s3, s3, 0
	global_store_dword v141, v100, s[2:3] offset:0
	global_store_dword v141, v101, s[2:3] offset:128
	s_add_u32 s2, s2, 0x1000
	s_addc_u32 s3, s3, 0
	global_store_dword v141, v102, s[2:3] offset:0
	global_store_dword v141, v103, s[2:3] offset:128
	s_add_u32 s2, s2, 0x5000
	s_addc_u32 s3, s3, 0
	global_store_dword v141, v104, s[2:3] offset:0
	global_store_dword v141, v105, s[2:3] offset:128
	s_add_u32 s2, s2, 0x1000
	s_addc_u32 s3, s3, 0
	global_store_dword v141, v106, s[2:3] offset:0
	global_store_dword v141, v107, s[2:3] offset:128
	s_add_u32 s2, s2, 0x1000
	s_addc_u32 s3, s3, 0
	global_store_dword v141, v108, s[2:3] offset:0
	global_store_dword v141, v109, s[2:3] offset:128
	s_add_u32 s2, s2, 0x1000
	s_addc_u32 s3, s3, 0
	global_store_dword v141, v110, s[2:3] offset:0
	global_store_dword v141, v111, s[2:3] offset:128
	s_add_u32 s2, s2, 0x5000
	s_addc_u32 s3, s3, 0
	global_store_dword v141, v112, s[2:3] offset:0
	global_store_dword v141, v113, s[2:3] offset:128
	s_add_u32 s2, s2, 0x1000
	s_addc_u32 s3, s3, 0
	global_store_dword v141, v114, s[2:3] offset:0
	global_store_dword v141, v115, s[2:3] offset:128
	s_add_u32 s2, s2, 0x1000
	s_addc_u32 s3, s3, 0
	global_store_dword v141, v116, s[2:3] offset:0
	global_store_dword v141, v117, s[2:3] offset:128
	s_add_u32 s2, s2, 0x1000
	s_addc_u32 s3, s3, 0
	global_store_dword v141, v118, s[2:3] offset:0
	global_store_dword v141, v119, s[2:3] offset:128
	s_add_u32 s2, s2, 0x5000
	s_addc_u32 s3, s3, 0
	global_store_dword v141, v120, s[2:3] offset:0
	global_store_dword v141, v121, s[2:3] offset:128
	s_add_u32 s2, s2, 0x1000
	s_addc_u32 s3, s3, 0
	global_store_dword v141, v122, s[2:3] offset:0
	global_store_dword v141, v123, s[2:3] offset:128
	s_add_u32 s2, s2, 0x1000
	s_addc_u32 s3, s3, 0
	global_store_dword v141, v124, s[2:3] offset:0
	global_store_dword v141, v125, s[2:3] offset:128
	s_add_u32 s2, s2, 0x1000
	s_addc_u32 s3, s3, 0
	global_store_dword v141, v126, s[2:3] offset:0
	global_store_dword v141, v127, s[2:3] offset:128
	s_branch .LBB0_1098
.Lep3_part:
	s_waitcnt vmcnt(0)
	v_mul_f32_e32 v64, v143, v48
	v_mul_f32_e32 v65, v144, v16
	v_mul_f32_e32 v66, v143, v49
	v_mul_f32_e32 v67, v144, v17
	v_mul_f32_e32 v68, v143, v50
	v_mul_f32_e32 v69, v144, v18
	v_mul_f32_e32 v70, v143, v51
	v_mul_f32_e32 v71, v144, v19
	v_mul_f32_e32 v72, v143, v52
	v_mul_f32_e32 v73, v144, v20
	v_mul_f32_e32 v74, v143, v53
	v_mul_f32_e32 v75, v144, v21
	v_mul_f32_e32 v76, v143, v54
	v_mul_f32_e32 v77, v144, v22
	v_mul_f32_e32 v78, v143, v55
	v_mul_f32_e32 v79, v144, v23
	v_mul_f32_e32 v80, v143, v56
	v_mul_f32_e32 v81, v144, v24
	v_mul_f32_e32 v82, v143, v57
	v_mul_f32_e32 v83, v144, v25
	v_mul_f32_e32 v84, v143, v58
	v_mul_f32_e32 v85, v144, v26
	v_mul_f32_e32 v86, v143, v59
	v_mul_f32_e32 v87, v144, v27
	v_mul_f32_e32 v88, v143, v60
	v_mul_f32_e32 v89, v144, v28
	v_mul_f32_e32 v90, v143, v61
	v_mul_f32_e32 v91, v144, v29
	v_mul_f32_e32 v92, v143, v62
	v_mul_f32_e32 v93, v144, v30
	v_mul_f32_e32 v94, v143, v63
	v_mul_f32_e32 v95, v144, v31
	v_mul_f32_e32 v96, v143, v32
	v_mul_f32_e32 v97, v144, v0
	v_mul_f32_e32 v98, v143, v33
	v_mul_f32_e32 v99, v144, v1
	v_mul_f32_e32 v100, v143, v34
	v_mul_f32_e32 v101, v144, v2
	v_mul_f32_e32 v102, v143, v35
	v_mul_f32_e32 v103, v144, v3
	v_mul_f32_e32 v104, v143, v36
	v_mul_f32_e32 v105, v144, v4
	v_mul_f32_e32 v106, v143, v37
	v_mul_f32_e32 v107, v144, v5
	v_mul_f32_e32 v108, v143, v38
	v_mul_f32_e32 v109, v144, v6
	v_mul_f32_e32 v110, v143, v39
	v_mul_f32_e32 v111, v144, v7
	v_mul_f32_e32 v112, v143, v40
	v_mul_f32_e32 v113, v144, v8
	v_mul_f32_e32 v114, v143, v41
	v_mul_f32_e32 v115, v144, v9
	v_mul_f32_e32 v116, v143, v42
	v_mul_f32_e32 v117, v144, v10
	v_mul_f32_e32 v118, v143, v43
	v_mul_f32_e32 v119, v144, v11
	v_mul_f32_e32 v120, v143, v44
	v_mul_f32_e32 v121, v144, v12
	v_mul_f32_e32 v122, v143, v45
	v_mul_f32_e32 v123, v144, v13
	v_mul_f32_e32 v124, v143, v46
	v_mul_f32_e32 v125, v144, v14
	v_mul_f32_e32 v126, v143, v47
	v_mul_f32_e32 v127, v144, v15
	s_mov_b32 s2, s98
	s_mov_b32 s3, s99
	global_atomic_add_f32 v141, v64, s[2:3] offset:0
	global_atomic_add_f32 v141, v65, s[2:3] offset:128
	s_add_u32 s2, s2, 0x1000
	s_addc_u32 s3, s3, 0
	global_atomic_add_f32 v141, v66, s[2:3] offset:0
	global_atomic_add_f32 v141, v67, s[2:3] offset:128
	s_add_u32 s2, s2, 0x1000
	s_addc_u32 s3, s3, 0
	global_atomic_add_f32 v141, v68, s[2:3] offset:0
	global_atomic_add_f32 v141, v69, s[2:3] offset:128
	s_add_u32 s2, s2, 0x1000
	s_addc_u32 s3, s3, 0
	global_atomic_add_f32 v141, v70, s[2:3] offset:0
	global_atomic_add_f32 v141, v71, s[2:3] offset:128
	s_add_u32 s2, s2, 0x5000
	s_addc_u32 s3, s3, 0
	global_atomic_add_f32 v141, v72, s[2:3] offset:0
	global_atomic_add_f32 v141, v73, s[2:3] offset:128
	s_add_u32 s2, s2, 0x1000
	s_addc_u32 s3, s3, 0
	global_atomic_add_f32 v141, v74, s[2:3] offset:0
	global_atomic_add_f32 v141, v75, s[2:3] offset:128
	s_add_u32 s2, s2, 0x1000
	s_addc_u32 s3, s3, 0
	global_atomic_add_f32 v141, v76, s[2:3] offset:0
	global_atomic_add_f32 v141, v77, s[2:3] offset:128
	s_add_u32 s2, s2, 0x1000
	s_addc_u32 s3, s3, 0
	global_atomic_add_f32 v141, v78, s[2:3] offset:0
	global_atomic_add_f32 v141, v79, s[2:3] offset:128
	s_add_u32 s2, s2, 0x5000
	s_addc_u32 s3, s3, 0
	global_atomic_add_f32 v141, v80, s[2:3] offset:0
	global_atomic_add_f32 v141, v81, s[2:3] offset:128
	s_add_u32 s2, s2, 0x1000
	s_addc_u32 s3, s3, 0
	global_atomic_add_f32 v141, v82, s[2:3] offset:0
	global_atomic_add_f32 v141, v83, s[2:3] offset:128
	s_add_u32 s2, s2, 0x1000
	s_addc_u32 s3, s3, 0
	global_atomic_add_f32 v141, v84, s[2:3] offset:0
	global_atomic_add_f32 v141, v85, s[2:3] offset:128
	s_add_u32 s2, s2, 0x1000
	s_addc_u32 s3, s3, 0
	global_atomic_add_f32 v141, v86, s[2:3] offset:0
	global_atomic_add_f32 v141, v87, s[2:3] offset:128
	s_add_u32 s2, s2, 0x5000
	s_addc_u32 s3, s3, 0
	global_atomic_add_f32 v141, v88, s[2:3] offset:0
	global_atomic_add_f32 v141, v89, s[2:3] offset:128
	s_add_u32 s2, s2, 0x1000
	s_addc_u32 s3, s3, 0
	global_atomic_add_f32 v141, v90, s[2:3] offset:0
	global_atomic_add_f32 v141, v91, s[2:3] offset:128
	s_add_u32 s2, s2, 0x1000
	s_addc_u32 s3, s3, 0
	global_atomic_add_f32 v141, v92, s[2:3] offset:0
	global_atomic_add_f32 v141, v93, s[2:3] offset:128
	s_add_u32 s2, s2, 0x1000
	s_addc_u32 s3, s3, 0
	global_atomic_add_f32 v141, v94, s[2:3] offset:0
	global_atomic_add_f32 v141, v95, s[2:3] offset:128
	s_add_u32 s2, s2, 0x5000
	s_addc_u32 s3, s3, 0
	global_atomic_add_f32 v141, v96, s[2:3] offset:0
	global_atomic_add_f32 v141, v97, s[2:3] offset:128
	s_add_u32 s2, s2, 0x1000
	s_addc_u32 s3, s3, 0
	global_atomic_add_f32 v141, v98, s[2:3] offset:0
	global_atomic_add_f32 v141, v99, s[2:3] offset:128
	s_add_u32 s2, s2, 0x1000
	s_addc_u32 s3, s3, 0
	global_atomic_add_f32 v141, v100, s[2:3] offset:0
	global_atomic_add_f32 v141, v101, s[2:3] offset:128
	s_add_u32 s2, s2, 0x1000
	s_addc_u32 s3, s3, 0
	global_atomic_add_f32 v141, v102, s[2:3] offset:0
	global_atomic_add_f32 v141, v103, s[2:3] offset:128
	s_add_u32 s2, s2, 0x5000
	s_addc_u32 s3, s3, 0
	global_atomic_add_f32 v141, v104, s[2:3] offset:0
	global_atomic_add_f32 v141, v105, s[2:3] offset:128
	s_add_u32 s2, s2, 0x1000
	s_addc_u32 s3, s3, 0
	global_atomic_add_f32 v141, v106, s[2:3] offset:0
	global_atomic_add_f32 v141, v107, s[2:3] offset:128
	s_add_u32 s2, s2, 0x1000
	s_addc_u32 s3, s3, 0
	global_atomic_add_f32 v141, v108, s[2:3] offset:0
	global_atomic_add_f32 v141, v109, s[2:3] offset:128
	s_add_u32 s2, s2, 0x1000
	s_addc_u32 s3, s3, 0
	global_atomic_add_f32 v141, v110, s[2:3] offset:0
	global_atomic_add_f32 v141, v111, s[2:3] offset:128
	s_add_u32 s2, s2, 0x5000
	s_addc_u32 s3, s3, 0
	global_atomic_add_f32 v141, v112, s[2:3] offset:0
	global_atomic_add_f32 v141, v113, s[2:3] offset:128
	s_add_u32 s2, s2, 0x1000
	s_addc_u32 s3, s3, 0
	global_atomic_add_f32 v141, v114, s[2:3] offset:0
	global_atomic_add_f32 v141, v115, s[2:3] offset:128
	s_add_u32 s2, s2, 0x1000
	s_addc_u32 s3, s3, 0
	global_atomic_add_f32 v141, v116, s[2:3] offset:0
	global_atomic_add_f32 v141, v117, s[2:3] offset:128
	s_add_u32 s2, s2, 0x1000
	s_addc_u32 s3, s3, 0
	global_atomic_add_f32 v141, v118, s[2:3] offset:0
	global_atomic_add_f32 v141, v119, s[2:3] offset:128
	s_add_u32 s2, s2, 0x5000
	s_addc_u32 s3, s3, 0
	global_atomic_add_f32 v141, v120, s[2:3] offset:0
	global_atomic_add_f32 v141, v121, s[2:3] offset:128
	s_add_u32 s2, s2, 0x1000
	s_addc_u32 s3, s3, 0
	global_atomic_add_f32 v141, v122, s[2:3] offset:0
	global_atomic_add_f32 v141, v123, s[2:3] offset:128
	s_add_u32 s2, s2, 0x1000
	s_addc_u32 s3, s3, 0
	global_atomic_add_f32 v141, v124, s[2:3] offset:0
	global_atomic_add_f32 v141, v125, s[2:3] offset:128
	s_add_u32 s2, s2, 0x1000
	s_addc_u32 s3, s3, 0
	global_atomic_add_f32 v141, v126, s[2:3] offset:0
	global_atomic_add_f32 v141, v127, s[2:3] offset:128
	s_branch .LBB0_1098

.LBB0_1882:
	v_lshl_or_b32 v136, v183, 3, v191
	v_and_b32_e32 v137, 31, v136
	v_bfe_u32 v138, v136, 6, 1
	v_mul_u32_u24_e32 v138, 64, v138
	v_add_u32_e32 v138, v138, v137
	v_lshlrev_b32_e32 v140, 2, v138
	v_bfe_u32 v138, v136, 7, 1
	v_lshlrev_b32_e32 v138, 4, v138
	v_bfe_u32 v143, v136, 5, 1
	v_or_b32_e32 v138, v138, v143
	v_lshl_add_u32 v139, v138, 14, v140
	s_sub_u32 s100, s9, 0x2000
	s_lshr_b32 s100, s100, 11
	s_add_u32 s100, s100, 1
	s_cmp_lt_u32 s9, 0x2000
	s_cmov_b32 s100, 0
	s_mul_i32 s100, s100, 0x6000
	s_lshl_b32 s101, s10, 2
	s_add_u32 s100, s100, s101
	s_add_u32 s100, s100, 0x3454000
	v_add_u32_e32 v140, s100, v140
	global_load_dword v141, v140, s[90:91]
	global_load_dword v142, v140, s[90:91] offset:128
	s_lshl_b32 s100, s9, 12
	s_add_u32 s100, s100, s101
	s_add_u32 s98, s88, s100
	s_addc_u32 s99, s89, 0
	s_and_b64 vcc, exec, s[36:37]
	s_cbranch_vccnz .Lep5_part
	s_mov_b32 s4, s98
	s_mov_b32 s5, s99
	global_load_dword v64, v139, s[4:5] offset:0
	global_load_dword v65, v139, s[4:5] offset:128
	s_add_u32 s4, s4, 0x1000
	s_addc_u32 s5, s5, 0
	global_load_dword v66, v139, s[4:5] offset:0
	global_load_dword v67, v139, s[4:5] offset:128
	s_add_u32 s4, s4, 0x1000
	s_addc_u32 s5, s5, 0
	global_load_dword v68, v139, s[4:5] offset:0
	global_load_dword v69, v139, s[4:5] offset:128
	s_add_u32 s4, s4, 0x1000
	s_addc_u32 s5, s5, 0
	global_load_dword v70, v139, s[4:5] offset:0
	global_load_dword v71, v139, s[4:5] offset:128
	s_add_u32 s4, s4, 0x5000
	s_addc_u32 s5, s5, 0
	global_load_dword v72, v139, s[4:5] offset:0
	global_load_dword v73, v139, s[4:5] offset:128
	s_add_u32 s4, s4, 0x1000
	s_addc_u32 s5, s5, 0
	global_load_dword v74, v139, s[4:5] offset:0
	global_load_dword v75, v139, s[4:5] offset:128
	s_add_u32 s4, s4, 0x1000
	s_addc_u32 s5, s5, 0
	global_load_dword v76, v139, s[4:5] offset:0
	global_load_dword v77, v139, s[4:5] offset:128
	s_add_u32 s4, s4, 0x1000
	s_addc_u32 s5, s5, 0
	global_load_dword v78, v139, s[4:5] offset:0
	global_load_dword v79, v139, s[4:5] offset:128
	s_add_u32 s4, s4, 0x5000
	s_addc_u32 s5, s5, 0
	global_load_dword v80, v139, s[4:5] offset:0
	global_load_dword v81, v139, s[4:5] offset:128
	s_add_u32 s4, s4, 0x1000
	s_addc_u32 s5, s5, 0
	global_load_dword v82, v139, s[4:5] offset:0
	global_load_dword v83, v139, s[4:5] offset:128
	s_add_u32 s4, s4, 0x1000
	s_addc_u32 s5, s5, 0
	global_load_dword v84, v139, s[4:5] offset:0
	global_load_dword v85, v139, s[4:5] offset:128
	s_add_u32 s4, s4, 0x1000
	s_addc_u32 s5, s5, 0
	global_load_dword v86, v139, s[4:5] offset:0
	global_load_dword v87, v139, s[4:5] offset:128
	s_add_u32 s4, s4, 0x5000
	s_addc_u32 s5, s5, 0
	global_load_dword v88, v139, s[4:5] offset:0
	global_load_dword v89, v139, s[4:5] offset:128
	s_add_u32 s4, s4, 0x1000
	s_addc_u32 s5, s5, 0
	global_load_dword v90, v139, s[4:5] offset:0
	global_load_dword v91, v139, s[4:5] offset:128
	s_add_u32 s4, s4, 0x1000
	s_addc_u32 s5, s5, 0
	global_load_dword v92, v139, s[4:5] offset:0
	global_load_dword v93, v139, s[4:5] offset:128
	s_add_u32 s4, s4, 0x1000
	s_addc_u32 s5, s5, 0
	global_load_dword v94, v139, s[4:5] offset:0
	global_load_dword v95, v139, s[4:5] offset:128
	s_add_u32 s4, s4, 0x5000
	s_addc_u32 s5, s5, 0
	global_load_dword v96, v139, s[4:5] offset:0
	global_load_dword v97, v139, s[4:5] offset:128
	s_add_u32 s4, s4, 0x1000
	s_addc_u32 s5, s5, 0
	global_load_dword v98, v139, s[4:5] offset:0
	global_load_dword v99, v139, s[4:5] offset:128
	s_add_u32 s4, s4, 0x1000
	s_addc_u32 s5, s5, 0
	global_load_dword v100, v139, s[4:5] offset:0
	global_load_dword v101, v139, s[4:5] offset:128
	s_add_u32 s4, s4, 0x1000
	s_addc_u32 s5, s5, 0
	global_load_dword v102, v139, s[4:5] offset:0
	global_load_dword v103, v139, s[4:5] offset:128
	s_add_u32 s4, s4, 0x5000
	s_addc_u32 s5, s5, 0
	global_load_dword v104, v139, s[4:5] offset:0
	global_load_dword v105, v139, s[4:5] offset:128
	s_add_u32 s4, s4, 0x1000
	s_addc_u32 s5, s5, 0
	global_load_dword v106, v139, s[4:5] offset:0
	global_load_dword v107, v139, s[4:5] offset:128
	s_add_u32 s4, s4, 0x1000
	s_addc_u32 s5, s5, 0
	global_load_dword v108, v139, s[4:5] offset:0
	global_load_dword v109, v139, s[4:5] offset:128
	s_add_u32 s4, s4, 0x1000
	s_addc_u32 s5, s5, 0
	global_load_dword v110, v139, s[4:5] offset:0
	global_load_dword v111, v139, s[4:5] offset:128
	s_add_u32 s4, s4, 0x5000
	s_addc_u32 s5, s5, 0
	global_load_dword v112, v139, s[4:5] offset:0
	global_load_dword v113, v139, s[4:5] offset:128
	s_add_u32 s4, s4, 0x1000
	s_addc_u32 s5, s5, 0
	global_load_dword v114, v139, s[4:5] offset:0
	global_load_dword v115, v139, s[4:5] offset:128
	s_add_u32 s4, s4, 0x1000
	s_addc_u32 s5, s5, 0
	global_load_dword v116, v139, s[4:5] offset:0
	global_load_dword v117, v139, s[4:5] offset:128
	s_add_u32 s4, s4, 0x1000
	s_addc_u32 s5, s5, 0
	global_load_dword v118, v139, s[4:5] offset:0
	global_load_dword v119, v139, s[4:5] offset:128
	s_add_u32 s4, s4, 0x5000
	s_addc_u32 s5, s5, 0
	global_load_dword v120, v139, s[4:5] offset:0
	global_load_dword v121, v139, s[4:5] offset:128
	s_add_u32 s4, s4, 0x1000
	s_addc_u32 s5, s5, 0
	global_load_dword v122, v139, s[4:5] offset:0
	global_load_dword v123, v139, s[4:5] offset:128
	s_add_u32 s4, s4, 0x1000
	s_addc_u32 s5, s5, 0
	global_load_dword v124, v139, s[4:5] offset:0
	global_load_dword v125, v139, s[4:5] offset:128
	s_add_u32 s4, s4, 0x1000
	s_addc_u32 s5, s5, 0
	global_load_dword v126, v139, s[4:5] offset:0
	global_load_dword v127, v139, s[4:5] offset:128
	s_waitcnt vmcnt(0)
	v_fmac_f32_e32 v64, v141, v48
	v_fmac_f32_e32 v65, v142, v16
	v_fmac_f32_e32 v66, v141, v49
	v_fmac_f32_e32 v67, v142, v17
	v_fmac_f32_e32 v68, v141, v50
	v_fmac_f32_e32 v69, v142, v18
	v_fmac_f32_e32 v70, v141, v51
	v_fmac_f32_e32 v71, v142, v19
	v_fmac_f32_e32 v72, v141, v52
	v_fmac_f32_e32 v73, v142, v20
	v_fmac_f32_e32 v74, v141, v53
	v_fmac_f32_e32 v75, v142, v21
	v_fmac_f32_e32 v76, v141, v54
	v_fmac_f32_e32 v77, v142, v22
	v_fmac_f32_e32 v78, v141, v55
	v_fmac_f32_e32 v79, v142, v23
	v_fmac_f32_e32 v80, v141, v56
	v_fmac_f32_e32 v81, v142, v24
	v_fmac_f32_e32 v82, v141, v57
	v_fmac_f32_e32 v83, v142, v25
	v_fmac_f32_e32 v84, v141, v58
	v_fmac_f32_e32 v85, v142, v26
	v_fmac_f32_e32 v86, v141, v59
	v_fmac_f32_e32 v87, v142, v27
	v_fmac_f32_e32 v88, v141, v60
	v_fmac_f32_e32 v89, v142, v28
	v_fmac_f32_e32 v90, v141, v61
	v_fmac_f32_e32 v91, v142, v29
	v_fmac_f32_e32 v92, v141, v62
	v_fmac_f32_e32 v93, v142, v30
	v_fmac_f32_e32 v94, v141, v63
	v_fmac_f32_e32 v95, v142, v31
	v_fmac_f32_e32 v96, v141, v32
	v_fmac_f32_e32 v97, v142, v0
	v_fmac_f32_e32 v98, v141, v33
	v_fmac_f32_e32 v99, v142, v1
	v_fmac_f32_e32 v100, v141, v34
	v_fmac_f32_e32 v101, v142, v2
	v_fmac_f32_e32 v102, v141, v35
	v_fmac_f32_e32 v103, v142, v3
	v_fmac_f32_e32 v104, v141, v36
	v_fmac_f32_e32 v105, v142, v4
	v_fmac_f32_e32 v106, v141, v37
	v_fmac_f32_e32 v107, v142, v5
	v_fmac_f32_e32 v108, v141, v38
	v_fmac_f32_e32 v109, v142, v6
	v_fmac_f32_e32 v110, v141, v39
	v_fmac_f32_e32 v111, v142, v7
	v_fmac_f32_e32 v112, v141, v40
	v_fmac_f32_e32 v113, v142, v8
	v_fmac_f32_e32 v114, v141, v41
	v_fmac_f32_e32 v115, v142, v9
	v_fmac_f32_e32 v116, v141, v42
	v_fmac_f32_e32 v117, v142, v10
	v_fmac_f32_e32 v118, v141, v43
	v_fmac_f32_e32 v119, v142, v11
	v_fmac_f32_e32 v120, v141, v44
	v_fmac_f32_e32 v121, v142, v12
	v_fmac_f32_e32 v122, v141, v45
	v_fmac_f32_e32 v123, v142, v13
	v_fmac_f32_e32 v124, v141, v46
	v_fmac_f32_e32 v125, v142, v14
	v_fmac_f32_e32 v126, v141, v47
	v_fmac_f32_e32 v127, v142, v15
	s_mov_b32 s4, s98
	s_mov_b32 s5, s99
	global_store_dword v139, v64, s[4:5] offset:0
	global_store_dword v139, v65, s[4:5] offset:128
	s_add_u32 s4, s4, 0x1000
	s_addc_u32 s5, s5, 0
	global_store_dword v139, v66, s[4:5] offset:0
	global_store_dword v139, v67, s[4:5] offset:128
	s_add_u32 s4, s4, 0x1000
	s_addc_u32 s5, s5, 0
	global_store_dword v139, v68, s[4:5] offset:0
	global_store_dword v139, v69, s[4:5] offset:128
	s_add_u32 s4, s4, 0x1000
	s_addc_u32 s5, s5, 0
	global_store_dword v139, v70, s[4:5] offset:0
	global_store_dword v139, v71, s[4:5] offset:128
	s_add_u32 s4, s4, 0x5000
	s_addc_u32 s5, s5, 0
	global_store_dword v139, v72, s[4:5] offset:0
	global_store_dword v139, v73, s[4:5] offset:128
	s_add_u32 s4, s4, 0x1000
	s_addc_u32 s5, s5, 0
	global_store_dword v139, v74, s[4:5] offset:0
	global_store_dword v139, v75, s[4:5] offset:128
	s_add_u32 s4, s4, 0x1000
	s_addc_u32 s5, s5, 0
	global_store_dword v139, v76, s[4:5] offset:0
	global_store_dword v139, v77, s[4:5] offset:128
	s_add_u32 s4, s4, 0x1000
	s_addc_u32 s5, s5, 0
	global_store_dword v139, v78, s[4:5] offset:0
	global_store_dword v139, v79, s[4:5] offset:128
	s_add_u32 s4, s4, 0x5000
	s_addc_u32 s5, s5, 0
	global_store_dword v139, v80, s[4:5] offset:0
	global_store_dword v139, v81, s[4:5] offset:128
	s_add_u32 s4, s4, 0x1000
	s_addc_u32 s5, s5, 0
	global_store_dword v139, v82, s[4:5] offset:0
	global_store_dword v139, v83, s[4:5] offset:128
	s_add_u32 s4, s4, 0x1000
	s_addc_u32 s5, s5, 0
	global_store_dword v139, v84, s[4:5] offset:0
	global_store_dword v139, v85, s[4:5] offset:128
	s_add_u32 s4, s4, 0x1000
	s_addc_u32 s5, s5, 0
	global_store_dword v139, v86, s[4:5] offset:0
	global_store_dword v139, v87, s[4:5] offset:128
	s_add_u32 s4, s4, 0x5000
	s_addc_u32 s5, s5, 0
	global_store_dword v139, v88, s[4:5] offset:0
	global_store_dword v139, v89, s[4:5] offset:128
	s_add_u32 s4, s4, 0x1000
	s_addc_u32 s5, s5, 0
	global_store_dword v139, v90, s[4:5] offset:0
	global_store_dword v139, v91, s[4:5] offset:128
	s_add_u32 s4, s4, 0x1000
	s_addc_u32 s5, s5, 0
	global_store_dword v139, v92, s[4:5] offset:0
	global_store_dword v139, v93, s[4:5] offset:128
	s_add_u32 s4, s4, 0x1000
	s_addc_u32 s5, s5, 0
	global_store_dword v139, v94, s[4:5] offset:0
	global_store_dword v139, v95, s[4:5] offset:128
	s_add_u32 s4, s4, 0x5000
	s_addc_u32 s5, s5, 0
	global_store_dword v139, v96, s[4:5] offset:0
	global_store_dword v139, v97, s[4:5] offset:128
	s_add_u32 s4, s4, 0x1000
	s_addc_u32 s5, s5, 0
	global_store_dword v139, v98, s[4:5] offset:0
	global_store_dword v139, v99, s[4:5] offset:128
	s_add_u32 s4, s4, 0x1000
	s_addc_u32 s5, s5, 0
	global_store_dword v139, v100, s[4:5] offset:0
	global_store_dword v139, v101, s[4:5] offset:128
	s_add_u32 s4, s4, 0x1000
	s_addc_u32 s5, s5, 0
	global_store_dword v139, v102, s[4:5] offset:0
	global_store_dword v139, v103, s[4:5] offset:128
	s_add_u32 s4, s4, 0x5000
	s_addc_u32 s5, s5, 0
	global_store_dword v139, v104, s[4:5] offset:0
	global_store_dword v139, v105, s[4:5] offset:128
	s_add_u32 s4, s4, 0x1000
	s_addc_u32 s5, s5, 0
	global_store_dword v139, v106, s[4:5] offset:0
	global_store_dword v139, v107, s[4:5] offset:128
	s_add_u32 s4, s4, 0x1000
	s_addc_u32 s5, s5, 0
	global_store_dword v139, v108, s[4:5] offset:0
	global_store_dword v139, v109, s[4:5] offset:128
	s_add_u32 s4, s4, 0x1000
	s_addc_u32 s5, s5, 0
	global_store_dword v139, v110, s[4:5] offset:0
	global_store_dword v139, v111, s[4:5] offset:128
	s_add_u32 s4, s4, 0x5000
	s_addc_u32 s5, s5, 0
	global_store_dword v139, v112, s[4:5] offset:0
	global_store_dword v139, v113, s[4:5] offset:128
	s_add_u32 s4, s4, 0x1000
	s_addc_u32 s5, s5, 0
	global_store_dword v139, v114, s[4:5] offset:0
	global_store_dword v139, v115, s[4:5] offset:128
	s_add_u32 s4, s4, 0x1000
	s_addc_u32 s5, s5, 0
	global_store_dword v139, v116, s[4:5] offset:0
	global_store_dword v139, v117, s[4:5] offset:128
	s_add_u32 s4, s4, 0x1000
	s_addc_u32 s5, s5, 0
	global_store_dword v139, v118, s[4:5] offset:0
	global_store_dword v139, v119, s[4:5] offset:128
	s_add_u32 s4, s4, 0x5000
	s_addc_u32 s5, s5, 0
	global_store_dword v139, v120, s[4:5] offset:0
	global_store_dword v139, v121, s[4:5] offset:128
	s_add_u32 s4, s4, 0x1000
	s_addc_u32 s5, s5, 0
	global_store_dword v139, v122, s[4:5] offset:0
	global_store_dword v139, v123, s[4:5] offset:128
	s_add_u32 s4, s4, 0x1000
	s_addc_u32 s5, s5, 0
	global_store_dword v139, v124, s[4:5] offset:0
	global_store_dword v139, v125, s[4:5] offset:128
	s_add_u32 s4, s4, 0x1000
	s_addc_u32 s5, s5, 0
	global_store_dword v139, v126, s[4:5] offset:0
	global_store_dword v139, v127, s[4:5] offset:128
	s_branch .LBB0_1873
.Lep5_part:
	s_waitcnt vmcnt(0)
	v_mul_f32_e32 v64, v141, v48
	v_mul_f32_e32 v65, v142, v16
	v_mul_f32_e32 v66, v141, v49
	v_mul_f32_e32 v67, v142, v17
	v_mul_f32_e32 v68, v141, v50
	v_mul_f32_e32 v69, v142, v18
	v_mul_f32_e32 v70, v141, v51
	v_mul_f32_e32 v71, v142, v19
	v_mul_f32_e32 v72, v141, v52
	v_mul_f32_e32 v73, v142, v20
	v_mul_f32_e32 v74, v141, v53
	v_mul_f32_e32 v75, v142, v21
	v_mul_f32_e32 v76, v141, v54
	v_mul_f32_e32 v77, v142, v22
	v_mul_f32_e32 v78, v141, v55
	v_mul_f32_e32 v79, v142, v23
	v_mul_f32_e32 v80, v141, v56
	v_mul_f32_e32 v81, v142, v24
	v_mul_f32_e32 v82, v141, v57
	v_mul_f32_e32 v83, v142, v25
	v_mul_f32_e32 v84, v141, v58
	v_mul_f32_e32 v85, v142, v26
	v_mul_f32_e32 v86, v141, v59
	v_mul_f32_e32 v87, v142, v27
	v_mul_f32_e32 v88, v141, v60
	v_mul_f32_e32 v89, v142, v28
	v_mul_f32_e32 v90, v141, v61
	v_mul_f32_e32 v91, v142, v29
	v_mul_f32_e32 v92, v141, v62
	v_mul_f32_e32 v93, v142, v30
	v_mul_f32_e32 v94, v141, v63
	v_mul_f32_e32 v95, v142, v31
	v_mul_f32_e32 v96, v141, v32
	v_mul_f32_e32 v97, v142, v0
	v_mul_f32_e32 v98, v141, v33
	v_mul_f32_e32 v99, v142, v1
	v_mul_f32_e32 v100, v141, v34
	v_mul_f32_e32 v101, v142, v2
	v_mul_f32_e32 v102, v141, v35
	v_mul_f32_e32 v103, v142, v3
	v_mul_f32_e32 v104, v141, v36
	v_mul_f32_e32 v105, v142, v4
	v_mul_f32_e32 v106, v141, v37
	v_mul_f32_e32 v107, v142, v5
	v_mul_f32_e32 v108, v141, v38
	v_mul_f32_e32 v109, v142, v6
	v_mul_f32_e32 v110, v141, v39
	v_mul_f32_e32 v111, v142, v7
	v_mul_f32_e32 v112, v141, v40
	v_mul_f32_e32 v113, v142, v8
	v_mul_f32_e32 v114, v141, v41
	v_mul_f32_e32 v115, v142, v9
	v_mul_f32_e32 v116, v141, v42
	v_mul_f32_e32 v117, v142, v10
	v_mul_f32_e32 v118, v141, v43
	v_mul_f32_e32 v119, v142, v11
	v_mul_f32_e32 v120, v141, v44
	v_mul_f32_e32 v121, v142, v12
	v_mul_f32_e32 v122, v141, v45
	v_mul_f32_e32 v123, v142, v13
	v_mul_f32_e32 v124, v141, v46
	v_mul_f32_e32 v125, v142, v14
	v_mul_f32_e32 v126, v141, v47
	v_mul_f32_e32 v127, v142, v15
	s_mov_b32 s4, s98
	s_mov_b32 s5, s99
	global_atomic_add_f32 v139, v64, s[4:5] offset:0
	global_atomic_add_f32 v139, v65, s[4:5] offset:128
	s_add_u32 s4, s4, 0x1000
	s_addc_u32 s5, s5, 0
	global_atomic_add_f32 v139, v66, s[4:5] offset:0
	global_atomic_add_f32 v139, v67, s[4:5] offset:128
	s_add_u32 s4, s4, 0x1000
	s_addc_u32 s5, s5, 0
	global_atomic_add_f32 v139, v68, s[4:5] offset:0
	global_atomic_add_f32 v139, v69, s[4:5] offset:128
	s_add_u32 s4, s4, 0x1000
	s_addc_u32 s5, s5, 0
	global_atomic_add_f32 v139, v70, s[4:5] offset:0
	global_atomic_add_f32 v139, v71, s[4:5] offset:128
	s_add_u32 s4, s4, 0x5000
	s_addc_u32 s5, s5, 0
	global_atomic_add_f32 v139, v72, s[4:5] offset:0
	global_atomic_add_f32 v139, v73, s[4:5] offset:128
	s_add_u32 s4, s4, 0x1000
	s_addc_u32 s5, s5, 0
	global_atomic_add_f32 v139, v74, s[4:5] offset:0
	global_atomic_add_f32 v139, v75, s[4:5] offset:128
	s_add_u32 s4, s4, 0x1000
	s_addc_u32 s5, s5, 0
	global_atomic_add_f32 v139, v76, s[4:5] offset:0
	global_atomic_add_f32 v139, v77, s[4:5] offset:128
	s_add_u32 s4, s4, 0x1000
	s_addc_u32 s5, s5, 0
	global_atomic_add_f32 v139, v78, s[4:5] offset:0
	global_atomic_add_f32 v139, v79, s[4:5] offset:128
	s_add_u32 s4, s4, 0x5000
	s_addc_u32 s5, s5, 0
	global_atomic_add_f32 v139, v80, s[4:5] offset:0
	global_atomic_add_f32 v139, v81, s[4:5] offset:128
	s_add_u32 s4, s4, 0x1000
	s_addc_u32 s5, s5, 0
	global_atomic_add_f32 v139, v82, s[4:5] offset:0
	global_atomic_add_f32 v139, v83, s[4:5] offset:128
	s_add_u32 s4, s4, 0x1000
	s_addc_u32 s5, s5, 0
	global_atomic_add_f32 v139, v84, s[4:5] offset:0
	global_atomic_add_f32 v139, v85, s[4:5] offset:128
	s_add_u32 s4, s4, 0x1000
	s_addc_u32 s5, s5, 0
	global_atomic_add_f32 v139, v86, s[4:5] offset:0
	global_atomic_add_f32 v139, v87, s[4:5] offset:128
	s_add_u32 s4, s4, 0x5000
	s_addc_u32 s5, s5, 0
	global_atomic_add_f32 v139, v88, s[4:5] offset:0
	global_atomic_add_f32 v139, v89, s[4:5] offset:128
	s_add_u32 s4, s4, 0x1000
	s_addc_u32 s5, s5, 0
	global_atomic_add_f32 v139, v90, s[4:5] offset:0
	global_atomic_add_f32 v139, v91, s[4:5] offset:128
	s_add_u32 s4, s4, 0x1000
	s_addc_u32 s5, s5, 0
	global_atomic_add_f32 v139, v92, s[4:5] offset:0
	global_atomic_add_f32 v139, v93, s[4:5] offset:128
	s_add_u32 s4, s4, 0x1000
	s_addc_u32 s5, s5, 0
	global_atomic_add_f32 v139, v94, s[4:5] offset:0
	global_atomic_add_f32 v139, v95, s[4:5] offset:128
	s_add_u32 s4, s4, 0x5000
	s_addc_u32 s5, s5, 0
	global_atomic_add_f32 v139, v96, s[4:5] offset:0
	global_atomic_add_f32 v139, v97, s[4:5] offset:128
	s_add_u32 s4, s4, 0x1000
	s_addc_u32 s5, s5, 0
	global_atomic_add_f32 v139, v98, s[4:5] offset:0
	global_atomic_add_f32 v139, v99, s[4:5] offset:128
	s_add_u32 s4, s4, 0x1000
	s_addc_u32 s5, s5, 0
	global_atomic_add_f32 v139, v100, s[4:5] offset:0
	global_atomic_add_f32 v139, v101, s[4:5] offset:128
	s_add_u32 s4, s4, 0x1000
	s_addc_u32 s5, s5, 0
	global_atomic_add_f32 v139, v102, s[4:5] offset:0
	global_atomic_add_f32 v139, v103, s[4:5] offset:128
	s_add_u32 s4, s4, 0x5000
	s_addc_u32 s5, s5, 0
	global_atomic_add_f32 v139, v104, s[4:5] offset:0
	global_atomic_add_f32 v139, v105, s[4:5] offset:128
	s_add_u32 s4, s4, 0x1000
	s_addc_u32 s5, s5, 0
	global_atomic_add_f32 v139, v106, s[4:5] offset:0
	global_atomic_add_f32 v139, v107, s[4:5] offset:128
	s_add_u32 s4, s4, 0x1000
	s_addc_u32 s5, s5, 0
	global_atomic_add_f32 v139, v108, s[4:5] offset:0
	global_atomic_add_f32 v139, v109, s[4:5] offset:128
	s_add_u32 s4, s4, 0x1000
	s_addc_u32 s5, s5, 0
	global_atomic_add_f32 v139, v110, s[4:5] offset:0
	global_atomic_add_f32 v139, v111, s[4:5] offset:128
	s_add_u32 s4, s4, 0x5000
	s_addc_u32 s5, s5, 0
	global_atomic_add_f32 v139, v112, s[4:5] offset:0
	global_atomic_add_f32 v139, v113, s[4:5] offset:128
	s_add_u32 s4, s4, 0x1000
	s_addc_u32 s5, s5, 0
	global_atomic_add_f32 v139, v114, s[4:5] offset:0
	global_atomic_add_f32 v139, v115, s[4:5] offset:128
	s_add_u32 s4, s4, 0x1000
	s_addc_u32 s5, s5, 0
	global_atomic_add_f32 v139, v116, s[4:5] offset:0
	global_atomic_add_f32 v139, v117, s[4:5] offset:128
	s_add_u32 s4, s4, 0x1000
	s_addc_u32 s5, s5, 0
	global_atomic_add_f32 v139, v118, s[4:5] offset:0
	global_atomic_add_f32 v139, v119, s[4:5] offset:128
	s_add_u32 s4, s4, 0x5000
	s_addc_u32 s5, s5, 0
	global_atomic_add_f32 v139, v120, s[4:5] offset:0
	global_atomic_add_f32 v139, v121, s[4:5] offset:128
	s_add_u32 s4, s4, 0x1000
	s_addc_u32 s5, s5, 0
	global_atomic_add_f32 v139, v122, s[4:5] offset:0
	global_atomic_add_f32 v139, v123, s[4:5] offset:128
	s_add_u32 s4, s4, 0x1000
	s_addc_u32 s5, s5, 0
	global_atomic_add_f32 v139, v124, s[4:5] offset:0
	global_atomic_add_f32 v139, v125, s[4:5] offset:128
	s_add_u32 s4, s4, 0x1000
	s_addc_u32 s5, s5, 0
	global_atomic_add_f32 v139, v126, s[4:5] offset:0
	global_atomic_add_f32 v139, v127, s[4:5] offset:128
	s_branch .LBB0_1873

.LBB0_2356:
	v_lshl_or_b32 v134, v183, 3, v191
	v_and_b32_e32 v135, 31, v134
	v_bfe_u32 v136, v134, 6, 1
	v_mul_u32_u24_e32 v136, 64, v136
	v_add_u32_e32 v136, v136, v135
	v_lshlrev_b32_e32 v138, 2, v136
	v_bfe_u32 v136, v134, 7, 1
	v_lshlrev_b32_e32 v136, 4, v136
	v_bfe_u32 v141, v134, 5, 1
	v_or_b32_e32 v136, v136, v141
	v_lshl_add_u32 v137, v136, 14, v138
	s_sub_u32 s100, s7, 0x2000
	s_lshr_b32 s100, s100, 11
	s_add_u32 s100, s100, 1
	s_cmp_lt_u32 s7, 0x2000
	s_cmov_b32 s100, 0
	s_mul_i32 s100, s100, 0x6000
	s_lshl_b32 s101, s8, 2
	s_add_u32 s100, s100, s101
	s_add_u32 s100, s100, 0x3457000
	v_add_u32_e32 v138, s100, v138
	global_load_dword v139, v138, s[90:91]
	global_load_dword v140, v138, s[90:91] offset:128
	s_lshl_b32 s100, s7, 12
	s_add_u32 s100, s100, s101
	s_add_u32 s98, s88, s100
	s_addc_u32 s99, s89, 0
	s_and_b64 vcc, exec, s[26:27]
	s_cbranch_vccnz .Lep7_part
	s_mov_b32 s2, s98
	s_mov_b32 s3, s99
	global_load_dword v64, v137, s[2:3] offset:0
	global_load_dword v65, v137, s[2:3] offset:128
	s_add_u32 s2, s2, 0x1000
	s_addc_u32 s3, s3, 0
	global_load_dword v66, v137, s[2:3] offset:0
	global_load_dword v67, v137, s[2:3] offset:128
	s_add_u32 s2, s2, 0x1000
	s_addc_u32 s3, s3, 0
	global_load_dword v68, v137, s[2:3] offset:0
	global_load_dword v69, v137, s[2:3] offset:128
	s_add_u32 s2, s2, 0x1000
	s_addc_u32 s3, s3, 0
	global_load_dword v70, v137, s[2:3] offset:0
	global_load_dword v71, v137, s[2:3] offset:128
	s_add_u32 s2, s2, 0x5000
	s_addc_u32 s3, s3, 0
	global_load_dword v72, v137, s[2:3] offset:0
	global_load_dword v73, v137, s[2:3] offset:128
	s_add_u32 s2, s2, 0x1000
	s_addc_u32 s3, s3, 0
	global_load_dword v74, v137, s[2:3] offset:0
	global_load_dword v75, v137, s[2:3] offset:128
	s_add_u32 s2, s2, 0x1000
	s_addc_u32 s3, s3, 0
	global_load_dword v76, v137, s[2:3] offset:0
	global_load_dword v77, v137, s[2:3] offset:128
	s_add_u32 s2, s2, 0x1000
	s_addc_u32 s3, s3, 0
	global_load_dword v78, v137, s[2:3] offset:0
	global_load_dword v79, v137, s[2:3] offset:128
	s_add_u32 s2, s2, 0x5000
	s_addc_u32 s3, s3, 0
	global_load_dword v80, v137, s[2:3] offset:0
	global_load_dword v81, v137, s[2:3] offset:128
	s_add_u32 s2, s2, 0x1000
	s_addc_u32 s3, s3, 0
	global_load_dword v82, v137, s[2:3] offset:0
	global_load_dword v83, v137, s[2:3] offset:128
	s_add_u32 s2, s2, 0x1000
	s_addc_u32 s3, s3, 0
	global_load_dword v84, v137, s[2:3] offset:0
	global_load_dword v85, v137, s[2:3] offset:128
	s_add_u32 s2, s2, 0x1000
	s_addc_u32 s3, s3, 0
	global_load_dword v86, v137, s[2:3] offset:0
	global_load_dword v87, v137, s[2:3] offset:128
	s_add_u32 s2, s2, 0x5000
	s_addc_u32 s3, s3, 0
	global_load_dword v88, v137, s[2:3] offset:0
	global_load_dword v89, v137, s[2:3] offset:128
	s_add_u32 s2, s2, 0x1000
	s_addc_u32 s3, s3, 0
	global_load_dword v90, v137, s[2:3] offset:0
	global_load_dword v91, v137, s[2:3] offset:128
	s_add_u32 s2, s2, 0x1000
	s_addc_u32 s3, s3, 0
	global_load_dword v92, v137, s[2:3] offset:0
	global_load_dword v93, v137, s[2:3] offset:128
	s_add_u32 s2, s2, 0x1000
	s_addc_u32 s3, s3, 0
	global_load_dword v94, v137, s[2:3] offset:0
	global_load_dword v95, v137, s[2:3] offset:128
	s_add_u32 s2, s2, 0x5000
	s_addc_u32 s3, s3, 0
	global_load_dword v96, v137, s[2:3] offset:0
	global_load_dword v97, v137, s[2:3] offset:128
	s_add_u32 s2, s2, 0x1000
	s_addc_u32 s3, s3, 0
	global_load_dword v98, v137, s[2:3] offset:0
	global_load_dword v99, v137, s[2:3] offset:128
	s_add_u32 s2, s2, 0x1000
	s_addc_u32 s3, s3, 0
	global_load_dword v100, v137, s[2:3] offset:0
	global_load_dword v101, v137, s[2:3] offset:128
	s_add_u32 s2, s2, 0x1000
	s_addc_u32 s3, s3, 0
	global_load_dword v102, v137, s[2:3] offset:0
	global_load_dword v103, v137, s[2:3] offset:128
	s_add_u32 s2, s2, 0x5000
	s_addc_u32 s3, s3, 0
	global_load_dword v104, v137, s[2:3] offset:0
	global_load_dword v105, v137, s[2:3] offset:128
	s_add_u32 s2, s2, 0x1000
	s_addc_u32 s3, s3, 0
	global_load_dword v106, v137, s[2:3] offset:0
	global_load_dword v107, v137, s[2:3] offset:128
	s_add_u32 s2, s2, 0x1000
	s_addc_u32 s3, s3, 0
	global_load_dword v108, v137, s[2:3] offset:0
	global_load_dword v109, v137, s[2:3] offset:128
	s_add_u32 s2, s2, 0x1000
	s_addc_u32 s3, s3, 0
	global_load_dword v110, v137, s[2:3] offset:0
	global_load_dword v111, v137, s[2:3] offset:128
	s_add_u32 s2, s2, 0x5000
	s_addc_u32 s3, s3, 0
	global_load_dword v112, v137, s[2:3] offset:0
	global_load_dword v113, v137, s[2:3] offset:128
	s_add_u32 s2, s2, 0x1000
	s_addc_u32 s3, s3, 0
	global_load_dword v114, v137, s[2:3] offset:0
	global_load_dword v115, v137, s[2:3] offset:128
	s_add_u32 s2, s2, 0x1000
	s_addc_u32 s3, s3, 0
	global_load_dword v116, v137, s[2:3] offset:0
	global_load_dword v117, v137, s[2:3] offset:128
	s_add_u32 s2, s2, 0x1000
	s_addc_u32 s3, s3, 0
	global_load_dword v118, v137, s[2:3] offset:0
	global_load_dword v119, v137, s[2:3] offset:128
	s_add_u32 s2, s2, 0x5000
	s_addc_u32 s3, s3, 0
	global_load_dword v120, v137, s[2:3] offset:0
	global_load_dword v121, v137, s[2:3] offset:128
	s_add_u32 s2, s2, 0x1000
	s_addc_u32 s3, s3, 0
	global_load_dword v122, v137, s[2:3] offset:0
	global_load_dword v123, v137, s[2:3] offset:128
	s_add_u32 s2, s2, 0x1000
	s_addc_u32 s3, s3, 0
	global_load_dword v124, v137, s[2:3] offset:0
	global_load_dword v125, v137, s[2:3] offset:128
	s_add_u32 s2, s2, 0x1000
	s_addc_u32 s3, s3, 0
	global_load_dword v126, v137, s[2:3] offset:0
	global_load_dword v127, v137, s[2:3] offset:128
	s_waitcnt vmcnt(0)
	v_fmac_f32_e32 v64, v139, v48
	v_fmac_f32_e32 v65, v140, v16
	v_fmac_f32_e32 v66, v139, v49
	v_fmac_f32_e32 v67, v140, v17
	v_fmac_f32_e32 v68, v139, v50
	v_fmac_f32_e32 v69, v140, v18
	v_fmac_f32_e32 v70, v139, v51
	v_fmac_f32_e32 v71, v140, v19
	v_fmac_f32_e32 v72, v139, v52
	v_fmac_f32_e32 v73, v140, v20
	v_fmac_f32_e32 v74, v139, v53
	v_fmac_f32_e32 v75, v140, v21
	v_fmac_f32_e32 v76, v139, v54
	v_fmac_f32_e32 v77, v140, v22
	v_fmac_f32_e32 v78, v139, v55
	v_fmac_f32_e32 v79, v140, v23
	v_fmac_f32_e32 v80, v139, v56
	v_fmac_f32_e32 v81, v140, v24
	v_fmac_f32_e32 v82, v139, v57
	v_fmac_f32_e32 v83, v140, v25
	v_fmac_f32_e32 v84, v139, v58
	v_fmac_f32_e32 v85, v140, v26
	v_fmac_f32_e32 v86, v139, v59
	v_fmac_f32_e32 v87, v140, v27
	v_fmac_f32_e32 v88, v139, v60
	v_fmac_f32_e32 v89, v140, v28
	v_fmac_f32_e32 v90, v139, v61
	v_fmac_f32_e32 v91, v140, v29
	v_fmac_f32_e32 v92, v139, v62
	v_fmac_f32_e32 v93, v140, v30
	v_fmac_f32_e32 v94, v139, v63
	v_fmac_f32_e32 v95, v140, v31
	v_fmac_f32_e32 v96, v139, v32
	v_fmac_f32_e32 v97, v140, v0
	v_fmac_f32_e32 v98, v139, v33
	v_fmac_f32_e32 v99, v140, v1
	v_fmac_f32_e32 v100, v139, v34
	v_fmac_f32_e32 v101, v140, v2
	v_fmac_f32_e32 v102, v139, v35
	v_fmac_f32_e32 v103, v140, v3
	v_fmac_f32_e32 v104, v139, v36
	v_fmac_f32_e32 v105, v140, v4
	v_fmac_f32_e32 v106, v139, v37
	v_fmac_f32_e32 v107, v140, v5
	v_fmac_f32_e32 v108, v139, v38
	v_fmac_f32_e32 v109, v140, v6
	v_fmac_f32_e32 v110, v139, v39
	v_fmac_f32_e32 v111, v140, v7
	v_fmac_f32_e32 v112, v139, v40
	v_fmac_f32_e32 v113, v140, v8
	v_fmac_f32_e32 v114, v139, v41
	v_fmac_f32_e32 v115, v140, v9
	v_fmac_f32_e32 v116, v139, v42
	v_fmac_f32_e32 v117, v140, v10
	v_fmac_f32_e32 v118, v139, v43
	v_fmac_f32_e32 v119, v140, v11
	v_fmac_f32_e32 v120, v139, v44
	v_fmac_f32_e32 v121, v140, v12
	v_fmac_f32_e32 v122, v139, v45
	v_fmac_f32_e32 v123, v140, v13
	v_fmac_f32_e32 v124, v139, v46
	v_fmac_f32_e32 v125, v140, v14
	v_fmac_f32_e32 v126, v139, v47
	v_fmac_f32_e32 v127, v140, v15
	s_mov_b32 s2, s98
	s_mov_b32 s3, s99
	global_store_dword v137, v64, s[2:3] offset:0
	global_store_dword v137, v65, s[2:3] offset:128
	s_add_u32 s2, s2, 0x1000
	s_addc_u32 s3, s3, 0
	global_store_dword v137, v66, s[2:3] offset:0
	global_store_dword v137, v67, s[2:3] offset:128
	s_add_u32 s2, s2, 0x1000
	s_addc_u32 s3, s3, 0
	global_store_dword v137, v68, s[2:3] offset:0
	global_store_dword v137, v69, s[2:3] offset:128
	s_add_u32 s2, s2, 0x1000
	s_addc_u32 s3, s3, 0
	global_store_dword v137, v70, s[2:3] offset:0
	global_store_dword v137, v71, s[2:3] offset:128
	s_add_u32 s2, s2, 0x5000
	s_addc_u32 s3, s3, 0
	global_store_dword v137, v72, s[2:3] offset:0
	global_store_dword v137, v73, s[2:3] offset:128
	s_add_u32 s2, s2, 0x1000
	s_addc_u32 s3, s3, 0
	global_store_dword v137, v74, s[2:3] offset:0
	global_store_dword v137, v75, s[2:3] offset:128
	s_add_u32 s2, s2, 0x1000
	s_addc_u32 s3, s3, 0
	global_store_dword v137, v76, s[2:3] offset:0
	global_store_dword v137, v77, s[2:3] offset:128
	s_add_u32 s2, s2, 0x1000
	s_addc_u32 s3, s3, 0
	global_store_dword v137, v78, s[2:3] offset:0
	global_store_dword v137, v79, s[2:3] offset:128
	s_add_u32 s2, s2, 0x5000
	s_addc_u32 s3, s3, 0
	global_store_dword v137, v80, s[2:3] offset:0
	global_store_dword v137, v81, s[2:3] offset:128
	s_add_u32 s2, s2, 0x1000
	s_addc_u32 s3, s3, 0
	global_store_dword v137, v82, s[2:3] offset:0
	global_store_dword v137, v83, s[2:3] offset:128
	s_add_u32 s2, s2, 0x1000
	s_addc_u32 s3, s3, 0
	global_store_dword v137, v84, s[2:3] offset:0
	global_store_dword v137, v85, s[2:3] offset:128
	s_add_u32 s2, s2, 0x1000
	s_addc_u32 s3, s3, 0
	global_store_dword v137, v86, s[2:3] offset:0
	global_store_dword v137, v87, s[2:3] offset:128
	s_add_u32 s2, s2, 0x5000
	s_addc_u32 s3, s3, 0
	global_store_dword v137, v88, s[2:3] offset:0
	global_store_dword v137, v89, s[2:3] offset:128
	s_add_u32 s2, s2, 0x1000
	s_addc_u32 s3, s3, 0
	global_store_dword v137, v90, s[2:3] offset:0
	global_store_dword v137, v91, s[2:3] offset:128
	s_add_u32 s2, s2, 0x1000
	s_addc_u32 s3, s3, 0
	global_store_dword v137, v92, s[2:3] offset:0
	global_store_dword v137, v93, s[2:3] offset:128
	s_add_u32 s2, s2, 0x1000
	s_addc_u32 s3, s3, 0
	global_store_dword v137, v94, s[2:3] offset:0
	global_store_dword v137, v95, s[2:3] offset:128
	s_add_u32 s2, s2, 0x5000
	s_addc_u32 s3, s3, 0
	global_store_dword v137, v96, s[2:3] offset:0
	global_store_dword v137, v97, s[2:3] offset:128
	s_add_u32 s2, s2, 0x1000
	s_addc_u32 s3, s3, 0
	global_store_dword v137, v98, s[2:3] offset:0
	global_store_dword v137, v99, s[2:3] offset:128
	s_add_u32 s2, s2, 0x1000
	s_addc_u32 s3, s3, 0
	global_store_dword v137, v100, s[2:3] offset:0
	global_store_dword v137, v101, s[2:3] offset:128
	s_add_u32 s2, s2, 0x1000
	s_addc_u32 s3, s3, 0
	global_store_dword v137, v102, s[2:3] offset:0
	global_store_dword v137, v103, s[2:3] offset:128
	s_add_u32 s2, s2, 0x5000
	s_addc_u32 s3, s3, 0
	global_store_dword v137, v104, s[2:3] offset:0
	global_store_dword v137, v105, s[2:3] offset:128
	s_add_u32 s2, s2, 0x1000
	s_addc_u32 s3, s3, 0
	global_store_dword v137, v106, s[2:3] offset:0
	global_store_dword v137, v107, s[2:3] offset:128
	s_add_u32 s2, s2, 0x1000
	s_addc_u32 s3, s3, 0
	global_store_dword v137, v108, s[2:3] offset:0
	global_store_dword v137, v109, s[2:3] offset:128
	s_add_u32 s2, s2, 0x1000
	s_addc_u32 s3, s3, 0
	global_store_dword v137, v110, s[2:3] offset:0
	global_store_dword v137, v111, s[2:3] offset:128
	s_add_u32 s2, s2, 0x5000
	s_addc_u32 s3, s3, 0
	global_store_dword v137, v112, s[2:3] offset:0
	global_store_dword v137, v113, s[2:3] offset:128
	s_add_u32 s2, s2, 0x1000
	s_addc_u32 s3, s3, 0
	global_store_dword v137, v114, s[2:3] offset:0
	global_store_dword v137, v115, s[2:3] offset:128
	s_add_u32 s2, s2, 0x1000
	s_addc_u32 s3, s3, 0
	global_store_dword v137, v116, s[2:3] offset:0
	global_store_dword v137, v117, s[2:3] offset:128
	s_add_u32 s2, s2, 0x1000
	s_addc_u32 s3, s3, 0
	global_store_dword v137, v118, s[2:3] offset:0
	global_store_dword v137, v119, s[2:3] offset:128
	s_add_u32 s2, s2, 0x5000
	s_addc_u32 s3, s3, 0
	global_store_dword v137, v120, s[2:3] offset:0
	global_store_dword v137, v121, s[2:3] offset:128
	s_add_u32 s2, s2, 0x1000
	s_addc_u32 s3, s3, 0
	global_store_dword v137, v122, s[2:3] offset:0
	global_store_dword v137, v123, s[2:3] offset:128
	s_add_u32 s2, s2, 0x1000
	s_addc_u32 s3, s3, 0
	global_store_dword v137, v124, s[2:3] offset:0
	global_store_dword v137, v125, s[2:3] offset:128
	s_add_u32 s2, s2, 0x1000
	s_addc_u32 s3, s3, 0
	global_store_dword v137, v126, s[2:3] offset:0
	global_store_dword v137, v127, s[2:3] offset:128
	s_branch .LBB0_2347
.Lep7_part:
	s_waitcnt vmcnt(0)
	v_mul_f32_e32 v64, v139, v48
	v_mul_f32_e32 v65, v140, v16
	v_mul_f32_e32 v66, v139, v49
	v_mul_f32_e32 v67, v140, v17
	v_mul_f32_e32 v68, v139, v50
	v_mul_f32_e32 v69, v140, v18
	v_mul_f32_e32 v70, v139, v51
	v_mul_f32_e32 v71, v140, v19
	v_mul_f32_e32 v72, v139, v52
	v_mul_f32_e32 v73, v140, v20
	v_mul_f32_e32 v74, v139, v53
	v_mul_f32_e32 v75, v140, v21
	v_mul_f32_e32 v76, v139, v54
	v_mul_f32_e32 v77, v140, v22
	v_mul_f32_e32 v78, v139, v55
	v_mul_f32_e32 v79, v140, v23
	v_mul_f32_e32 v80, v139, v56
	v_mul_f32_e32 v81, v140, v24
	v_mul_f32_e32 v82, v139, v57
	v_mul_f32_e32 v83, v140, v25
	v_mul_f32_e32 v84, v139, v58
	v_mul_f32_e32 v85, v140, v26
	v_mul_f32_e32 v86, v139, v59
	v_mul_f32_e32 v87, v140, v27
	v_mul_f32_e32 v88, v139, v60
	v_mul_f32_e32 v89, v140, v28
	v_mul_f32_e32 v90, v139, v61
	v_mul_f32_e32 v91, v140, v29
	v_mul_f32_e32 v92, v139, v62
	v_mul_f32_e32 v93, v140, v30
	v_mul_f32_e32 v94, v139, v63
	v_mul_f32_e32 v95, v140, v31
	v_mul_f32_e32 v96, v139, v32
	v_mul_f32_e32 v97, v140, v0
	v_mul_f32_e32 v98, v139, v33
	v_mul_f32_e32 v99, v140, v1
	v_mul_f32_e32 v100, v139, v34
	v_mul_f32_e32 v101, v140, v2
	v_mul_f32_e32 v102, v139, v35
	v_mul_f32_e32 v103, v140, v3
	v_mul_f32_e32 v104, v139, v36
	v_mul_f32_e32 v105, v140, v4
	v_mul_f32_e32 v106, v139, v37
	v_mul_f32_e32 v107, v140, v5
	v_mul_f32_e32 v108, v139, v38
	v_mul_f32_e32 v109, v140, v6
	v_mul_f32_e32 v110, v139, v39
	v_mul_f32_e32 v111, v140, v7
	v_mul_f32_e32 v112, v139, v40
	v_mul_f32_e32 v113, v140, v8
	v_mul_f32_e32 v114, v139, v41
	v_mul_f32_e32 v115, v140, v9
	v_mul_f32_e32 v116, v139, v42
	v_mul_f32_e32 v117, v140, v10
	v_mul_f32_e32 v118, v139, v43
	v_mul_f32_e32 v119, v140, v11
	v_mul_f32_e32 v120, v139, v44
	v_mul_f32_e32 v121, v140, v12
	v_mul_f32_e32 v122, v139, v45
	v_mul_f32_e32 v123, v140, v13
	v_mul_f32_e32 v124, v139, v46
	v_mul_f32_e32 v125, v140, v14
	v_mul_f32_e32 v126, v139, v47
	v_mul_f32_e32 v127, v140, v15
	s_mov_b32 s2, s98
	s_mov_b32 s3, s99
	global_atomic_add_f32 v137, v64, s[2:3] offset:0
	global_atomic_add_f32 v137, v65, s[2:3] offset:128
	s_add_u32 s2, s2, 0x1000
	s_addc_u32 s3, s3, 0
	global_atomic_add_f32 v137, v66, s[2:3] offset:0
	global_atomic_add_f32 v137, v67, s[2:3] offset:128
	s_add_u32 s2, s2, 0x1000
	s_addc_u32 s3, s3, 0
	global_atomic_add_f32 v137, v68, s[2:3] offset:0
	global_atomic_add_f32 v137, v69, s[2:3] offset:128
	s_add_u32 s2, s2, 0x1000
	s_addc_u32 s3, s3, 0
	global_atomic_add_f32 v137, v70, s[2:3] offset:0
	global_atomic_add_f32 v137, v71, s[2:3] offset:128
	s_add_u32 s2, s2, 0x5000
	s_addc_u32 s3, s3, 0
	global_atomic_add_f32 v137, v72, s[2:3] offset:0
	global_atomic_add_f32 v137, v73, s[2:3] offset:128
	s_add_u32 s2, s2, 0x1000
	s_addc_u32 s3, s3, 0
	global_atomic_add_f32 v137, v74, s[2:3] offset:0
	global_atomic_add_f32 v137, v75, s[2:3] offset:128
	s_add_u32 s2, s2, 0x1000
	s_addc_u32 s3, s3, 0
	global_atomic_add_f32 v137, v76, s[2:3] offset:0
	global_atomic_add_f32 v137, v77, s[2:3] offset:128
	s_add_u32 s2, s2, 0x1000
	s_addc_u32 s3, s3, 0
	global_atomic_add_f32 v137, v78, s[2:3] offset:0
	global_atomic_add_f32 v137, v79, s[2:3] offset:128
	s_add_u32 s2, s2, 0x5000
	s_addc_u32 s3, s3, 0
	global_atomic_add_f32 v137, v80, s[2:3] offset:0
	global_atomic_add_f32 v137, v81, s[2:3] offset:128
	s_add_u32 s2, s2, 0x1000
	s_addc_u32 s3, s3, 0
	global_atomic_add_f32 v137, v82, s[2:3] offset:0
	global_atomic_add_f32 v137, v83, s[2:3] offset:128
	s_add_u32 s2, s2, 0x1000
	s_addc_u32 s3, s3, 0
	global_atomic_add_f32 v137, v84, s[2:3] offset:0
	global_atomic_add_f32 v137, v85, s[2:3] offset:128
	s_add_u32 s2, s2, 0x1000
	s_addc_u32 s3, s3, 0
	global_atomic_add_f32 v137, v86, s[2:3] offset:0
	global_atomic_add_f32 v137, v87, s[2:3] offset:128
	s_add_u32 s2, s2, 0x5000
	s_addc_u32 s3, s3, 0
	global_atomic_add_f32 v137, v88, s[2:3] offset:0
	global_atomic_add_f32 v137, v89, s[2:3] offset:128
	s_add_u32 s2, s2, 0x1000
	s_addc_u32 s3, s3, 0
	global_atomic_add_f32 v137, v90, s[2:3] offset:0
	global_atomic_add_f32 v137, v91, s[2:3] offset:128
	s_add_u32 s2, s2, 0x1000
	s_addc_u32 s3, s3, 0
	global_atomic_add_f32 v137, v92, s[2:3] offset:0
	global_atomic_add_f32 v137, v93, s[2:3] offset:128
	s_add_u32 s2, s2, 0x1000
	s_addc_u32 s3, s3, 0
	global_atomic_add_f32 v137, v94, s[2:3] offset:0
	global_atomic_add_f32 v137, v95, s[2:3] offset:128
	s_add_u32 s2, s2, 0x5000
	s_addc_u32 s3, s3, 0
	global_atomic_add_f32 v137, v96, s[2:3] offset:0
	global_atomic_add_f32 v137, v97, s[2:3] offset:128
	s_add_u32 s2, s2, 0x1000
	s_addc_u32 s3, s3, 0
	global_atomic_add_f32 v137, v98, s[2:3] offset:0
	global_atomic_add_f32 v137, v99, s[2:3] offset:128
	s_add_u32 s2, s2, 0x1000
	s_addc_u32 s3, s3, 0
	global_atomic_add_f32 v137, v100, s[2:3] offset:0
	global_atomic_add_f32 v137, v101, s[2:3] offset:128
	s_add_u32 s2, s2, 0x1000
	s_addc_u32 s3, s3, 0
	global_atomic_add_f32 v137, v102, s[2:3] offset:0
	global_atomic_add_f32 v137, v103, s[2:3] offset:128
	s_add_u32 s2, s2, 0x5000
	s_addc_u32 s3, s3, 0
	global_atomic_add_f32 v137, v104, s[2:3] offset:0
	global_atomic_add_f32 v137, v105, s[2:3] offset:128
	s_add_u32 s2, s2, 0x1000
	s_addc_u32 s3, s3, 0
	global_atomic_add_f32 v137, v106, s[2:3] offset:0
	global_atomic_add_f32 v137, v107, s[2:3] offset:128
	s_add_u32 s2, s2, 0x1000
	s_addc_u32 s3, s3, 0
	global_atomic_add_f32 v137, v108, s[2:3] offset:0
	global_atomic_add_f32 v137, v109, s[2:3] offset:128
	s_add_u32 s2, s2, 0x1000
	s_addc_u32 s3, s3, 0
	global_atomic_add_f32 v137, v110, s[2:3] offset:0
	global_atomic_add_f32 v137, v111, s[2:3] offset:128
	s_add_u32 s2, s2, 0x5000
	s_addc_u32 s3, s3, 0
	global_atomic_add_f32 v137, v112, s[2:3] offset:0
	global_atomic_add_f32 v137, v113, s[2:3] offset:128
	s_add_u32 s2, s2, 0x1000
	s_addc_u32 s3, s3, 0
	global_atomic_add_f32 v137, v114, s[2:3] offset:0
	global_atomic_add_f32 v137, v115, s[2:3] offset:128
	s_add_u32 s2, s2, 0x1000
	s_addc_u32 s3, s3, 0
	global_atomic_add_f32 v137, v116, s[2:3] offset:0
	global_atomic_add_f32 v137, v117, s[2:3] offset:128
	s_add_u32 s2, s2, 0x1000
	s_addc_u32 s3, s3, 0
	global_atomic_add_f32 v137, v118, s[2:3] offset:0
	global_atomic_add_f32 v137, v119, s[2:3] offset:128
	s_add_u32 s2, s2, 0x5000
	s_addc_u32 s3, s3, 0
	global_atomic_add_f32 v137, v120, s[2:3] offset:0
	global_atomic_add_f32 v137, v121, s[2:3] offset:128
	s_add_u32 s2, s2, 0x1000
	s_addc_u32 s3, s3, 0
	global_atomic_add_f32 v137, v122, s[2:3] offset:0
	global_atomic_add_f32 v137, v123, s[2:3] offset:128
	s_add_u32 s2, s2, 0x1000
	s_addc_u32 s3, s3, 0
	global_atomic_add_f32 v137, v124, s[2:3] offset:0
	global_atomic_add_f32 v137, v125, s[2:3] offset:128
	s_add_u32 s2, s2, 0x1000
	s_addc_u32 s3, s3, 0
	global_atomic_add_f32 v137, v126, s[2:3] offset:0
	global_atomic_add_f32 v137, v127, s[2:3] offset:128
	s_branch .LBB0_2347
